# XCD-aware permutation of all mixers-phase items (mLSTM, position-DFT and final-state tiles): same-XCD workgroups get contiguous items, on top of v29
# speedup vs baseline: 1.0137x; 1.0023x over previous
.LBB0_591:
	s_or_b64 exec, exec, s[0:1]
	s_mov_b64 s[0:1], s[86:87]
	s_mov_b32 s33, s84
	s_mov_b32 s100, s84
	s_waitcnt lgkmcnt(0)
	s_barrier
	s_cmpk_gt_i32 s33, 0xcff
	s_cbranch_scc1 .LBB0_660
	s_load_dwordx4 s[8:11], s[0:1], 0x98
	s_load_dwordx4 s[12:15], s[0:1], 0x20
	s_mov_b32 s0, s46
	s_mov_b32 s69, 0xfffffc0
	s_waitcnt lgkmcnt(0)
	s_add_u32 s44, s10, 0x21bd8000
	s_addc_u32 s45, s11, 0
	s_add_u32 s46, s10, 0xd998000
	s_addc_u32 s47, s11, 0
	s_add_u32 s48, s10, 0xc198000
	s_addc_u32 s49, s11, 0
	s_add_u32 s50, s10, 0x1bbd8000
	s_addc_u32 s51, s11, 0
	s_add_u32 s52, s10, 0x55c0000
	s_addc_u32 s53, s11, 0
	s_add_u32 s54, s10, 0x5600000
	s_addc_u32 s55, s11, 0
	s_add_u32 s70, s10, 0x18b78000
	s_addc_u32 s1, s11, 0
	s_add_u32 s58, s10, 0x9198000
	s_addc_u32 s59, s11, 0
	s_add_u32 s60, s10, 0x1cbd8000
	s_addc_u32 s61, s11, 0
	s_lshl_b32 s62, s0, 1
	s_add_u32 s63, s8, 0x3000000
	s_addc_u32 s64, s9, 0
	s_add_u32 s0, s10, 0xa998000
	v_writelane_b32 v255, s1, 9
	s_addc_u32 s1, s11, 0
	s_add_u32 s65, s10, 0xe198000
	s_addc_u32 s66, s11, 0
	s_add_u32 s67, s10, 0x18a58000
	s_addc_u32 s68, s11, 0
	s_add_u32 s6, s10, 0x18ab8000
	s_addc_u32 s7, s11, 0
	s_add_u32 s34, s10, 0x18b18000
	s_addc_u32 s35, s11, 0
	s_add_u32 s16, s10, 0x22bd8000
	s_addc_u32 s17, s11, 0
	s_add_u32 s20, s10, 0x18bd8000
	s_addc_u32 s21, s11, 0
	s_add_u32 s36, s10, 0xc198800
	s_addc_u32 s37, s11, 0
	s_add_u32 s2, s10, 0x18b78010
	v_writelane_b32 v255, s2, 10
	s_addc_u32 s2, s11, 0
	v_writelane_b32 v255, s2, 12
	s_branch .LBB0_595

.LBB0_594:
	s_load_dword s2, s[90:91], 0x0
	s_waitcnt lgkmcnt(0)
	s_add_i32 s100, s2, s100
	s_cmpk_lt_i32 s100, 0xd00
	s_cbranch_scc0 .LBB0_659
.LBB0_595:
	s_mov_b32 s33, s100
	s_cmpk_gt_u32 s100, 0xbff
	s_cbranch_scc1 .Lxcd_noperm
	s_and_b32 s33, s100, 7
	s_lshl_b32 s33, s33, 6
	s_bfe_u32 s2, s100, 0x60003
	s_or_b32 s33, s33, s2
	s_and_b32 s2, s100, 0xfffffe00
	s_or_b32 s33, s33, s2

	.amdhsa_kernel _Z10fwd_kernel6Params
		.amdhsa_group_segment_fixed_size 74768
		.amdhsa_private_segment_fixed_size 0
		.amdhsa_kernarg_size 424
		.amdhsa_user_sgpr_count 2
		.amdhsa_user_sgpr_dispatch_ptr 0
		.amdhsa_user_sgpr_queue_ptr 0
		.amdhsa_user_sgpr_kernarg_segment_ptr 1
		.amdhsa_user_sgpr_dispatch_id 0
		.amdhsa_user_sgpr_kernarg_preload_length 0
		.amdhsa_user_sgpr_kernarg_preload_offset 0
		.amdhsa_user_sgpr_private_segment_size 0
		.amdhsa_uses_dynamic_stack 0
		.amdhsa_enable_private_segment 0
		.amdhsa_system_sgpr_workgroup_id_x 1
		.amdhsa_system_sgpr_workgroup_id_y 0
		.amdhsa_system_sgpr_workgroup_id_z 0
		.amdhsa_system_sgpr_workgroup_info 0
		.amdhsa_system_vgpr_workitem_id 2
		.amdhsa_next_free_vgpr 256
		.amdhsa_next_free_sgpr 102
		.amdhsa_accum_offset 256
		.amdhsa_reserve_vcc 1
		.amdhsa_float_round_mode_32 0
		.amdhsa_float_round_mode_16_64 0
		.amdhsa_float_denorm_mode_32 3
		.amdhsa_float_denorm_mode_16_64 3
		.amdhsa_dx10_clamp 1
		.amdhsa_ieee_mode 1
		.amdhsa_fp16_overflow 0
		.amdhsa_tg_split 0
		.amdhsa_exception_fp_ieee_invalid_op 0
		.amdhsa_exception_fp_denorm_src 0
		.amdhsa_exception_fp_ieee_div_zero 0
		.amdhsa_exception_fp_ieee_overflow 0
		.amdhsa_exception_fp_ieee_underflow 0
		.amdhsa_exception_fp_ieee_inexact 0
		.amdhsa_exception_int_div_zero 0
	.end_amdhsa_kernel

amdhsa.kernels:
  - .agpr_count:     0
    .args:
      - .offset:         0
        .size:           168
        .value_kind:     by_value
      - .offset:         168
        .size:           4
        .value_kind:     hidden_block_count_x
      - .offset:         172
        .size:           4
        .value_kind:     hidden_block_count_y
      - .offset:         176
        .size:           4
        .value_kind:     hidden_block_count_z
      - .offset:         180
        .size:           2
        .value_kind:     hidden_group_size_x
      - .offset:         182
        .size:           2
        .value_kind:     hidden_group_size_y
      - .offset:         184
        .size:           2
        .value_kind:     hidden_group_size_z
      - .offset:         186
        .size:           2
        .value_kind:     hidden_remainder_x
      - .offset:         188
        .size:           2
        .value_kind:     hidden_remainder_y
      - .offset:         190
        .size:           2
        .value_kind:     hidden_remainder_z
      - .offset:         208
        .size:           8
        .value_kind:     hidden_global_offset_x
      - .offset:         216
        .size:           8
        .value_kind:     hidden_global_offset_y
      - .offset:         224
        .size:           8
        .value_kind:     hidden_global_offset_z
      - .offset:         232
        .size:           2
        .value_kind:     hidden_grid_dims
      - .offset:         256
        .size:           8
        .value_kind:     hidden_multigrid_sync_arg
    .group_segment_fixed_size: 74768
    .kernarg_segment_align: 8
    .kernarg_segment_size: 424
    .language:       OpenCL C
    .language_version:
      - 2
      - 0
    .max_flat_workgroup_size: 256
    .name:           _Z10fwd_kernel6Params
    .private_segment_fixed_size: 0
    .sgpr_count:     108
    .sgpr_spill_count: 81
    .symbol:         _Z10fwd_kernel6Params.kd
    .uniform_work_group_size: 1
    .uses_dynamic_stack: false
    .vgpr_count:     256
    .vgpr_spill_count: 0
    .wavefront_size: 64
